# diff and attn constant-shift loops: symmetric per-cluster s_setprio flips removed, one static raise for waves 4-7
# baseline (speedup 1.0000x reference)
.LBB0_745:
	v_mov_b32_e32 v177, v192
	v_lshl_add_u64 v[18:19], v[172:173], 1, v[18:19]
	v_ashrrev_i32_e32 v22, 31, v177
	v_lshrrev_b32_e32 v22, 28, v22
	v_add_u32_e32 v22, v177, v22
	v_ashrrev_i32_e32 v50, 4, v22
	v_and_b32_e32 v22, -16, v22
	v_sub_u32_e32 v58, v177, v22
	v_lshlrev_b32_e32 v24, 3, v58
	v_ashrrev_i32_e32 v25, 31, v24
	v_add_u32_e32 v34, 0x200, v177
	v_and_b32_e32 v113, 31, v177
	v_bfe_u32 v51, v177, 5, 1
	v_lshlrev_b64 v[52:53], 1, v[24:25]
	v_ashrrev_i32_e32 v24, 31, v34
	v_mad_u64_u32 v[18:19], s[24:25], v113, s28, v[18:19]
	v_lshlrev_b32_e32 v174, 4, v51
	v_mov_b32_e32 v175, v112
	v_lshrrev_b32_e32 v24, 28, v24
	v_lshl_add_u64 v[46:47], v[18:19], 0, v[174:175]
	v_add_u32_e32 v24, v34, v24
	global_load_dwordx4 v[18:21], v[46:47], off offset:96
	v_ashrrev_i32_e32 v54, 4, v24
	v_and_b32_e32 v24, -16, v24
	v_sub_u32_e32 v59, v34, v24
	v_lshlrev_b32_e32 v26, 3, v59
	v_ashrrev_i32_e32 v62, 3, v177
	v_lshlrev_b32_e32 v32, 3, v177
	v_ashrrev_i32_e32 v63, 3, v34
	v_mad_i64_i32 v[22:23], s[24:25], s22, v50, 0
	v_mad_i64_i32 v[24:25], s[24:25], s22, v54, 0
	v_ashrrev_i32_e32 v27, 31, v26
	v_mad_i64_i32 v[30:31], s[24:25], s20, v62, 0
	v_and_b32_e32 v55, 56, v32
	v_mad_i64_i32 v[34:35], s[24:25], s20, v63, 0
	v_lshl_add_u64 v[22:23], v[22:23], 1, v[180:181]
	v_lshl_add_u64 v[24:25], v[24:25], 1, v[180:181]
	v_lshlrev_b64 v[56:57], 1, v[26:27]
	v_lshl_add_u64 v[30:31], v[30:31], 1, v[16:17]
	v_lshlrev_b32_e32 v32, 1, v55
	v_mov_b32_e32 v33, v112
	v_lshl_add_u64 v[34:35], v[34:35], 1, v[16:17]
	v_lshl_add_u64 v[22:23], v[22:23], 0, v[52:53]
	v_lshl_add_u64 v[26:27], v[24:25], 0, v[56:57]
	v_lshl_add_u64 v[30:31], v[30:31], 0, v[32:33]
	v_lshl_add_u64 v[34:35], v[34:35], 0, v[32:33]
	global_load_dwordx4 v[22:25], v[22:23], off
	s_nop 0
	global_load_dwordx4 v[26:29], v[26:27], off
	s_nop 0
	global_load_dwordx4 v[30:33], v[30:31], off
	s_nop 0
	global_load_dwordx4 v[34:37], v[34:35], off
	s_nop 0
	global_load_dwordx4 v[38:41], v[46:47], off offset:64
	global_load_dwordx4 v[42:45], v[46:47], off offset:32
	s_nop 0
	global_load_dwordx4 v[46:49], v[46:47], off
	v_lshlrev_b32_e32 v201, 4, v58
	v_lshlrev_b32_e32 v213, 4, v59
	s_mov_b32 s24, 0x3e38aa3b
	s_movk_i32 s1, 0x48
	v_lshlrev_b32_e32 v176, 3, v51
	v_mul_lo_u32 v51, v62, s1
	v_add_lshl_u32 v191, v51, v55, 1
	v_mul_lo_u32 v51, v63, s1
	s_movk_i32 s1, 0x110
	v_mul_lo_u32 v195, v50, s1
	v_mul_lo_u32 v202, v54, s1
	s_lshl_b32 s1, s20, 1
	v_add_lshl_u32 v193, v51, v55, 1
	v_ashrrev_i32_e32 v55, 31, v54
	v_lshl_add_u64 v[16:17], v[16:17], 0, s[94:95]
	v_ashrrev_i32_e32 v51, 31, v50
	v_add_u32_e32 v64, 0, v191
	v_add_u32_e32 v65, 0, v193
	v_add3_u32 v66, 0, v201, v195
	v_add3_u32 v67, 0, v213, v202
	v_mov_b32_e32 v190, 0
	v_and_b32_e32 v175, 63, v177
	v_mul_u32_u24_e32 v214, 0x90, v113
	s_add_i32 s0, s0, 1
	s_mov_b32 s5, 0
	v_mov_b32_e32 v68, v190
	v_mov_b32_e32 v69, v190
	v_mov_b32_e32 v70, v190
	v_mov_b32_e32 v71, v190
	v_mov_b32_e32 v72, v190
	v_mov_b32_e32 v73, v190
	v_mov_b32_e32 v74, v190
	v_mov_b32_e32 v75, v190
	v_mov_b32_e32 v76, v190
	v_mov_b32_e32 v77, v190
	v_mov_b32_e32 v78, v190
	v_mov_b32_e32 v79, v190
	s_waitcnt vmcnt(0)
	ds_write_b128 v66, v[22:25]
	ds_write_b128 v67, v[26:29]
	ds_write_b128 v64, v[30:33] offset:17408
	ds_write_b128 v65, v[34:37] offset:17408
	v_lshlrev_b32_e32 v58, 16, v18
	v_and_b32_e32 v59, 0xffff0000, v18
	v_lshlrev_b32_e32 v18, 16, v19
	v_and_b32_e32 v19, 0xffff0000, v19
	v_pk_mul_f32 v[18:19], v[18:19], s[24:25] op_sel_hi:[1,0]
	v_lshlrev_b32_e32 v60, 16, v20
	v_cvt_pk_bf16_f32 v115, v18, v19
	v_lshlrev_b32_e32 v18, 16, v21
	v_and_b32_e32 v19, 0xffff0000, v21
	v_pk_mul_f32 v[18:19], v[18:19], s[24:25] op_sel_hi:[1,0]
	v_and_b32_e32 v61, 0xffff0000, v20
	v_cvt_pk_bf16_f32 v117, v18, v19
	v_lshlrev_b32_e32 v18, 16, v38
	v_and_b32_e32 v19, 0xffff0000, v38
	v_pk_mul_f32 v[18:19], v[18:19], s[24:25] op_sel_hi:[1,0]
	v_pk_mul_f32 v[58:59], v[58:59], s[24:25] op_sel_hi:[1,0]
	v_cvt_pk_bf16_f32 v118, v18, v19
	v_lshlrev_b32_e32 v18, 16, v39
	v_and_b32_e32 v19, 0xffff0000, v39
	v_pk_mul_f32 v[18:19], v[18:19], s[24:25] op_sel_hi:[1,0]
	v_pk_mul_f32 v[60:61], v[60:61], s[24:25] op_sel_hi:[1,0]
	v_cvt_pk_bf16_f32 v119, v18, v19
	v_lshlrev_b32_e32 v18, 16, v40
	v_and_b32_e32 v19, 0xffff0000, v40
	v_pk_mul_f32 v[18:19], v[18:19], s[24:25] op_sel_hi:[1,0]
	v_cvt_pk_bf16_f32 v114, v58, v59
	v_cvt_pk_bf16_f32 v120, v18, v19
	v_lshlrev_b32_e32 v18, 16, v41
	v_and_b32_e32 v19, 0xffff0000, v41
	v_pk_mul_f32 v[18:19], v[18:19], s[24:25] op_sel_hi:[1,0]
	v_cvt_pk_bf16_f32 v116, v60, v61
	v_cvt_pk_bf16_f32 v121, v18, v19
	v_lshlrev_b32_e32 v18, 16, v42
	v_and_b32_e32 v19, 0xffff0000, v42
	v_pk_mul_f32 v[18:19], v[18:19], s[24:25] op_sel_hi:[1,0]
	v_mov_b32_e32 v22, v190
	v_cvt_pk_bf16_f32 v122, v18, v19
	v_lshlrev_b32_e32 v18, 16, v43
	v_and_b32_e32 v19, 0xffff0000, v43
	v_pk_mul_f32 v[18:19], v[18:19], s[24:25] op_sel_hi:[1,0]
	v_mov_b32_e32 v23, v190
	v_cvt_pk_bf16_f32 v123, v18, v19
	v_lshlrev_b32_e32 v18, 16, v44
	v_and_b32_e32 v19, 0xffff0000, v44
	v_pk_mul_f32 v[18:19], v[18:19], s[24:25] op_sel_hi:[1,0]
	v_mov_b32_e32 v24, v190
	v_cvt_pk_bf16_f32 v124, v18, v19
	v_lshlrev_b32_e32 v18, 16, v45
	v_and_b32_e32 v19, 0xffff0000, v45
	v_pk_mul_f32 v[18:19], v[18:19], s[24:25] op_sel_hi:[1,0]
	v_mov_b32_e32 v25, v190
	v_cvt_pk_bf16_f32 v125, v18, v19
	v_lshlrev_b32_e32 v18, 16, v46
	v_and_b32_e32 v19, 0xffff0000, v46
	v_pk_mul_f32 v[18:19], v[18:19], s[24:25] op_sel_hi:[1,0]
	v_mov_b32_e32 v26, v190
	v_cvt_pk_bf16_f32 v126, v18, v19
	v_lshlrev_b32_e32 v18, 16, v47
	v_and_b32_e32 v19, 0xffff0000, v47
	v_pk_mul_f32 v[18:19], v[18:19], s[24:25] op_sel_hi:[1,0]
	v_mov_b32_e32 v27, v190
	v_cvt_pk_bf16_f32 v127, v18, v19
	v_lshlrev_b32_e32 v18, 16, v48
	v_and_b32_e32 v19, 0xffff0000, v48
	v_pk_mul_f32 v[18:19], v[18:19], s[24:25] op_sel_hi:[1,0]
	v_mov_b32_e32 v28, v190
	v_cvt_pk_bf16_f32 v128, v18, v19
	v_lshlrev_b32_e32 v18, 16, v49
	v_and_b32_e32 v19, 0xffff0000, v49
	v_pk_mul_f32 v[18:19], v[18:19], s[24:25] op_sel_hi:[1,0]
	v_mov_b32_e32 v29, v190
	v_cvt_pk_bf16_f32 v129, v18, v19
	v_mul_u32_u24_e32 v18, 0x88, v113
	v_add_lshl_u32 v216, v18, v172, 1
	v_and_b32_e32 v18, 7, v177
	v_lshlrev_b32_e32 v18, 4, v18
	v_mov_b32_e32 v19, v112
	v_mad_i64_i32 v[20:21], s[20:21], s1, v63, v[18:19]
	v_mad_i64_i32 v[18:19], s[20:21], s1, v62, v[18:19]
	v_lshl_add_u64 v[182:183], v[16:17], 0, v[20:21]
	v_lshl_add_u64 v[184:185], v[16:17], 0, v[18:19]
	v_lshl_add_u64 v[16:17], v[54:55], 1, v[168:169]
	v_mad_u64_u32 v[186:187], s[20:21], s22, v16, v[56:57]
	v_mad_i32_i24 v187, s22, v17, v187
	v_lshl_add_u64 v[16:17], v[50:51], 1, v[168:169]
	v_mad_u64_u32 v[188:189], s[24:25], s22, v16, v[52:53]
	v_add_u32_e32 v215, 0x2200, v216
	s_lshl_b32 s20, s22, 7
	s_mov_b32 s21, s96
	v_mad_i32_i24 v189, s22, v17, v189
	v_mov_b32_e32 v16, 0
	v_mov_b32_e32 v17, v190
	v_mov_b32_e32 v18, v190
	v_mov_b32_e32 v19, v190
	v_mov_b32_e32 v20, v190
	v_mov_b32_e32 v21, v190
	v_mov_b32_e32 v30, v190
	v_mov_b32_e32 v31, v190
	v_mov_b32_e32 v32, 0
	v_mov_b32_e32 v33, v190
	v_mov_b32_e32 v34, v190
	v_mov_b32_e32 v35, v190
	v_mov_b32_e32 v36, v190
	v_mov_b32_e32 v37, v190
	v_mov_b32_e32 v38, v190
	v_mov_b32_e32 v39, v190
	v_mov_b32_e32 v40, v190
	v_mov_b32_e32 v41, v190
	v_mov_b32_e32 v42, v190
	v_mov_b32_e32 v43, v190
	v_mov_b32_e32 v44, v190
	v_mov_b32_e32 v45, v190
	v_mov_b32_e32 v46, v190
	v_mov_b32_e32 v47, v190
	v_mov_b32_e32 v48, 0
	v_mov_b32_e32 v49, v190
	v_mov_b32_e32 v50, v190
	v_mov_b32_e32 v51, v190
	v_mov_b32_e32 v52, v190
	v_mov_b32_e32 v53, v190
	v_mov_b32_e32 v54, v190
	v_mov_b32_e32 v55, v190
	v_mov_b32_e32 v56, v190
	v_mov_b32_e32 v57, v190
	v_mov_b32_e32 v58, v190
	v_mov_b32_e32 v59, v190
	v_mov_b32_e32 v60, v190
	v_mov_b32_e32 v61, v190
	v_mov_b32_e32 v62, v190
	v_mov_b32_e32 v63, v190
	v_mov_b32_e32 v64, 0
	v_mov_b32_e32 v65, v190
	v_mov_b32_e32 v66, v190
	v_mov_b32_e32 v67, v190
	s_waitcnt lgkmcnt(0)
	s_barrier
	v_readfirstlane_b32 s1, v192
	s_nop 0
	s_cmp_ge_u32 s1, 0x100
	s_cbranch_scc0 .Ldiff_prio_skip
	s_setprio 1
.Ldiff_prio_skip:
.LBB0_746:
	v_lshl_add_u64 v[80:81], v[180:181], 0, v[188:189]
	v_lshl_add_u64 v[82:83], v[180:181], 0, v[186:187]
	global_load_dwordx4 v[130:133], v[80:81], off
	global_load_dwordx4 v[134:137], v[82:83], off
	global_load_dwordx4 v[138:141], v[184:185], off
	global_load_dwordx4 v[142:145], v[182:183], off
	s_add_i32 s1, s5, 1
	s_bitcmp1_b32 s5, 0
	s_cselect_b32 s5, 0x8c00, 0
	s_add_i32 s5, s5, 0
	v_add_u32_e32 v84, s5, v174
	v_add_u32_e32 v85, v84, v216
	v_add_u32_e32 v84, v84, v215
	ds_read_b128 v[80:83], v85
	ds_read_b128 v[218:221], v85 offset:32
	ds_read_b128 v[222:225], v85 offset:64
	ds_read_b128 v[226:229], v85 offset:96
	ds_read_b128 v[230:233], v84
	ds_read_b128 v[234:237], v84 offset:32
	ds_read_b128 v[238:241], v84 offset:64
	ds_read_b128 v[242:245], v84 offset:96
	v_add3_u32 v84, s5, v176, v214
	v_add_u32_e32 v164, 0x4000, v84
	v_add_u32_e32 v165, 0x5000, v84
	v_add_u32_e32 v166, 0x6800, v84
	v_add_u32_e32 v167, 0x7800, v84
	ds_read2_b64 v[146:149], v164 offset0:128 offset1:130
	ds_read2_b64 v[150:153], v165 offset0:192 offset1:194
	ds_read2_b64 v[154:157], v166 offset1:2
	ds_read2_b64 v[158:161], v167 offset0:64 offset1:66
	s_waitcnt lgkmcnt(11)
	v_mfma_f32_32x32x16_bf16 v[96:111], v[80:83], v[126:129], v[0:15]
	s_waitcnt lgkmcnt(7)
	v_mfma_f32_32x32x16_bf16 v[80:95], v[230:233], v[126:129], v[0:15]
	v_mfma_f32_32x32x16_bf16 v[96:111], v[218:221], v[122:125], v[96:111]
	s_waitcnt lgkmcnt(6)
	v_mfma_f32_32x32x16_bf16 v[80:95], v[234:237], v[122:125], v[80:95]
	v_mfma_f32_32x32x16_bf16 v[96:111], v[222:225], v[118:121], v[96:111]
	s_waitcnt lgkmcnt(5)
	v_mfma_f32_32x32x16_bf16 v[80:95], v[238:241], v[118:121], v[80:95]
	v_mfma_f32_32x32x16_bf16 v[96:111], v[226:229], v[114:117], v[96:111]
	s_waitcnt lgkmcnt(4)
	v_mfma_f32_32x32x16_bf16 v[80:95], v[242:245], v[114:117], v[80:95]
	s_nop 8
	v_exp_f32_e32 v96, v96
	v_exp_f32_e32 v97, v97
	v_exp_f32_e32 v98, v98
	v_exp_f32_e32 v99, v99
	v_add_f32_e32 v194, 0, v96
	v_exp_f32_e32 v100, v100
	v_add_f32_e32 v194, v97, v194
	v_exp_f32_e32 v101, v101
	v_add_f32_e32 v194, v98, v194
	v_exp_f32_e32 v102, v102
	v_add_f32_e32 v194, v99, v194
	v_exp_f32_e32 v103, v103
	v_add_f32_e32 v194, v100, v194
	v_exp_f32_e32 v209, v104
	v_add_f32_e32 v194, v101, v194
	v_add_f32_e32 v194, v102, v194
	v_add_f32_e32 v194, v103, v194
	v_add_f32_e32 v104, v209, v194
	v_exp_f32_e32 v194, v105
	v_exp_f32_e32 v217, v106
	v_exp_f32_e32 v218, v107
	v_exp_f32_e32 v219, v108
	v_add_f32_e32 v104, v194, v104
	v_exp_f32_e32 v220, v109
	v_add_f32_e32 v104, v217, v104
	v_exp_f32_e32 v221, v110
	v_add_f32_e32 v104, v218, v104
	v_exp_f32_e32 v222, v111
	v_add_f32_e32 v104, v219, v104
	v_exp_f32_e32 v223, v80
	v_add_f32_e32 v104, v220, v104
	v_exp_f32_e32 v224, v81
	v_add_f32_e32 v104, v221, v104
	v_exp_f32_e32 v225, v82
	v_add_f32_e32 v104, v222, v104
	v_exp_f32_e32 v226, v83
	v_add_f32_e32 v80, v223, v104
	v_exp_f32_e32 v227, v84
	v_add_f32_e32 v80, v224, v80
	v_exp_f32_e32 v228, v85
	v_add_f32_e32 v80, v225, v80
	v_exp_f32_e32 v229, v86
	v_add_f32_e32 v80, v226, v80
	v_exp_f32_e32 v230, v87
	v_add_f32_e32 v80, v227, v80
	v_exp_f32_e32 v231, v88
	v_add_f32_e32 v80, v228, v80
	v_exp_f32_e32 v232, v89
	v_add_f32_e32 v80, v229, v80
	v_exp_f32_e32 v233, v90
	v_add_f32_e32 v80, v230, v80
	v_exp_f32_e32 v234, v91
	v_add_f32_e32 v80, v231, v80
	v_exp_f32_e32 v235, v92
	v_add_f32_e32 v80, v232, v80
	v_exp_f32_e32 v236, v93
	v_add_f32_e32 v80, v233, v80
	v_exp_f32_e32 v237, v94
	v_add_f32_e32 v80, v234, v80
	v_exp_f32_e32 v238, v95
	v_add_f32_e32 v80, v235, v80
	v_add_f32_e32 v80, v236, v80
	v_add_f32_e32 v80, v237, v80
	v_add_f32_e32 v80, v238, v80
	v_add_f32_e32 v190, v190, v80
	ds_read2_b64 v[80:83], v164 offset0:132 offset1:134
	ds_read2_b64 v[84:87], v165 offset0:196 offset1:198
	ds_read2_b64 v[88:91], v166 offset0:4 offset1:6
	ds_read2_b64 v[92:95], v167 offset0:68 offset1:70
	v_cvt_pk_bf16_f32 v96, v96, v97
	v_cvt_pk_bf16_f32 v97, v98, v99
	v_cvt_pk_bf16_f32 v98, v100, v101
	v_cvt_pk_bf16_f32 v99, v102, v103
	s_waitcnt lgkmcnt(7)
	v_mfma_f32_32x32x16_bf16 v[64:79], v[146:149], v[96:99], v[64:79]
	s_waitcnt lgkmcnt(6)
	v_mfma_f32_32x32x16_bf16 v[48:63], v[150:153], v[96:99], v[48:63]
	s_waitcnt lgkmcnt(5)
	v_mfma_f32_32x32x16_bf16 v[32:47], v[154:157], v[96:99], v[32:47]
	s_waitcnt lgkmcnt(4)
	v_mfma_f32_32x32x16_bf16 v[16:31], v[158:161], v[96:99], v[16:31]
	ds_read2_b64 v[96:99], v164 offset0:136 offset1:138
	ds_read2_b64 v[100:103], v165 offset0:200 offset1:202
	ds_read2_b64 v[104:107], v166 offset0:8 offset1:10
	ds_read2_b64 v[108:111], v167 offset0:72 offset1:74
	v_cvt_pk_bf16_f32 v146, v209, v194
	v_cvt_pk_bf16_f32 v147, v217, v218
	v_cvt_pk_bf16_f32 v148, v219, v220
	v_cvt_pk_bf16_f32 v149, v221, v222
	s_waitcnt lgkmcnt(7)
	v_mfma_f32_32x32x16_bf16 v[64:79], v[80:83], v[146:149], v[64:79]
	s_waitcnt lgkmcnt(6)
	v_mfma_f32_32x32x16_bf16 v[48:63], v[84:87], v[146:149], v[48:63]
	s_waitcnt lgkmcnt(5)
	v_mfma_f32_32x32x16_bf16 v[32:47], v[88:91], v[146:149], v[32:47]
	s_waitcnt lgkmcnt(4)
	v_mfma_f32_32x32x16_bf16 v[16:31], v[92:95], v[146:149], v[16:31]
	ds_read2_b64 v[80:83], v164 offset0:140 offset1:142
	ds_read2_b64 v[84:87], v165 offset0:204 offset1:206
	ds_read2_b64 v[88:91], v166 offset0:12 offset1:14
	ds_read2_b64 v[92:95], v167 offset0:76 offset1:78
	v_cvt_pk_bf16_f32 v146, v223, v224
	v_cvt_pk_bf16_f32 v147, v225, v226
	v_cvt_pk_bf16_f32 v148, v227, v228
	v_cvt_pk_bf16_f32 v149, v229, v230
	s_waitcnt lgkmcnt(7)
	v_mfma_f32_32x32x16_bf16 v[64:79], v[96:99], v[146:149], v[64:79]
	s_waitcnt lgkmcnt(6)
	v_mfma_f32_32x32x16_bf16 v[48:63], v[100:103], v[146:149], v[48:63]
	s_waitcnt lgkmcnt(5)
	v_mfma_f32_32x32x16_bf16 v[32:47], v[104:107], v[146:149], v[32:47]
	s_waitcnt lgkmcnt(4)
	v_mfma_f32_32x32x16_bf16 v[16:31], v[108:111], v[146:149], v[16:31]
	v_cvt_pk_bf16_f32 v96, v231, v232
	v_cvt_pk_bf16_f32 v97, v233, v234
	v_cvt_pk_bf16_f32 v98, v235, v236
	v_cvt_pk_bf16_f32 v99, v237, v238
	s_waitcnt lgkmcnt(3)
	v_mfma_f32_32x32x16_bf16 v[64:79], v[80:83], v[96:99], v[64:79]
	s_waitcnt lgkmcnt(2)
	v_mfma_f32_32x32x16_bf16 v[48:63], v[84:87], v[96:99], v[48:63]
	s_waitcnt lgkmcnt(1)
	v_mfma_f32_32x32x16_bf16 v[32:47], v[88:91], v[96:99], v[32:47]
	s_waitcnt lgkmcnt(0)
	v_mfma_f32_32x32x16_bf16 v[16:31], v[92:95], v[96:99], v[16:31]
	s_bitcmp1_b32 s1, 0
	s_cselect_b32 s5, 0x8c00, 0
	s_add_i32 s22, s5, 0
	v_add3_u32 v80, s22, v201, v195
	v_lshl_add_u64 v[182:183], v[182:183], 0, s[94:95]
	v_lshl_add_u64 v[184:185], v[184:185], 0, s[94:95]
	v_lshl_add_u64 v[180:181], v[180:181], 0, s[20:21]
	s_cmp_eq_u32 s0, s1
	s_mov_b32 s5, s1
	v_add3_u32 v81, s22, v213, v202
	v_add_u32_e32 v82, s22, v191
	v_add_u32_e32 v83, s22, v193
	s_waitcnt vmcnt(3)
	ds_write_b128 v80, v[130:133]
	s_waitcnt vmcnt(2)
	ds_write_b128 v81, v[134:137]
	s_waitcnt vmcnt(1)
	ds_write_b128 v82, v[138:141] offset:17408
	s_waitcnt vmcnt(0)
	ds_write_b128 v83, v[142:145] offset:17408
	s_waitcnt lgkmcnt(0)
	s_barrier
	s_cbranch_scc0 .LBB0_746
	v_add_u32_e32 v84, s22, v174
	v_add_u32_e32 v85, v84, v216
	v_add_u32_e32 v84, v84, v215
	ds_read_b128 v[80:83], v85
	ds_read_b128 v[146:149], v85 offset:32
	ds_read_b128 v[150:153], v85 offset:64
	ds_read_b128 v[154:157], v85 offset:96
	ds_read_b128 v[158:161], v84
	ds_read_b128 v[180:183], v84 offset:32
	ds_read_b128 v[184:187], v84 offset:64
	ds_read_b128 v[216:219], v84 offset:96
	v_add3_u32 v84, s22, v176, v214
	v_add_u32_e32 v164, 0x4000, v84
	v_add_u32_e32 v165, 0x5000, v84
	v_add_u32_e32 v166, 0x6800, v84
	v_add_u32_e32 v167, 0x7800, v84
	ds_read2_b64 v[130:133], v164 offset0:128 offset1:130
	ds_read2_b64 v[134:137], v165 offset0:192 offset1:194
	ds_read2_b64 v[138:141], v166 offset1:2
	ds_read2_b64 v[142:145], v167 offset0:64 offset1:66
	s_setprio 1
	s_waitcnt lgkmcnt(11)
	v_mfma_f32_32x32x16_bf16 v[96:111], v[80:83], v[126:129], v[0:15]
	s_waitcnt lgkmcnt(7)
	v_mfma_f32_32x32x16_bf16 v[80:95], v[158:161], v[126:129], v[0:15]
	s_waitcnt lgkmcnt(6)
	v_mfma_f32_32x32x16_bf16 v[80:95], v[180:183], v[122:125], v[80:95]
	v_mfma_f32_32x32x16_bf16 v[96:111], v[146:149], v[122:125], v[96:111]
	s_waitcnt lgkmcnt(5)
	v_mfma_f32_32x32x16_bf16 v[80:95], v[184:187], v[118:121], v[80:95]
	v_mfma_f32_32x32x16_bf16 v[96:111], v[150:153], v[118:121], v[96:111]
	s_waitcnt lgkmcnt(4)
	v_mfma_f32_32x32x16_bf16 v[80:95], v[216:219], v[114:117], v[80:95]
	v_mfma_f32_32x32x16_bf16 v[96:111], v[154:157], v[114:117], v[96:111]
	s_setprio 0
	s_nop 10
	v_exp_f32_e32 v96, v96
	v_exp_f32_e32 v97, v97
	v_exp_f32_e32 v98, v98
	v_exp_f32_e32 v99, v99
	v_add_f32_e32 v114, 0, v96
	v_exp_f32_e32 v100, v100
	v_add_f32_e32 v114, v97, v114
	v_exp_f32_e32 v101, v101
	v_add_f32_e32 v114, v98, v114
	v_exp_f32_e32 v102, v102
	v_add_f32_e32 v114, v99, v114
	v_exp_f32_e32 v103, v103
	v_add_f32_e32 v114, v100, v114
	v_exp_f32_e32 v115, v104
	v_add_f32_e32 v114, v101, v114
	v_add_f32_e32 v114, v102, v114
	v_add_f32_e32 v114, v103, v114
	v_add_f32_e32 v104, v115, v114
	v_exp_f32_e32 v114, v105
	v_exp_f32_e32 v116, v106
	v_exp_f32_e32 v117, v107
	v_exp_f32_e32 v118, v108
	v_add_f32_e32 v104, v114, v104
	v_exp_f32_e32 v119, v109
	v_add_f32_e32 v104, v116, v104
	v_exp_f32_e32 v120, v110
	v_add_f32_e32 v104, v117, v104
	v_exp_f32_e32 v121, v111
	v_add_f32_e32 v104, v118, v104
	v_exp_f32_e32 v122, v80
	v_add_f32_e32 v104, v119, v104
	v_exp_f32_e32 v123, v81
	v_add_f32_e32 v104, v120, v104
	v_exp_f32_e32 v124, v82
	v_add_f32_e32 v104, v121, v104
	v_exp_f32_e32 v125, v83
	v_add_f32_e32 v80, v122, v104
	v_exp_f32_e32 v126, v84
	v_add_f32_e32 v80, v123, v80
	v_exp_f32_e32 v127, v85
	v_add_f32_e32 v80, v124, v80
	v_exp_f32_e32 v128, v86
	v_add_f32_e32 v80, v125, v80
	v_exp_f32_e32 v129, v87
	v_add_f32_e32 v80, v126, v80
	v_exp_f32_e32 v146, v88
	v_add_f32_e32 v80, v127, v80
	v_exp_f32_e32 v147, v89
	v_add_f32_e32 v80, v128, v80
	v_exp_f32_e32 v148, v90
	v_add_f32_e32 v80, v129, v80
	v_exp_f32_e32 v149, v91
	v_add_f32_e32 v80, v146, v80
	v_exp_f32_e32 v150, v92
	v_add_f32_e32 v80, v147, v80
	v_exp_f32_e32 v151, v93
	v_add_f32_e32 v80, v148, v80
	v_exp_f32_e32 v152, v94
	v_add_f32_e32 v80, v149, v80
	v_exp_f32_e32 v153, v95
	v_add_f32_e32 v80, v150, v80
	v_add_f32_e32 v80, v151, v80
	v_add_f32_e32 v80, v152, v80
	v_add_f32_e32 v80, v153, v80
	v_add_f32_e32 v154, v190, v80
	ds_read2_b64 v[80:83], v164 offset0:132 offset1:134
	ds_read2_b64 v[84:87], v165 offset0:196 offset1:198
	ds_read2_b64 v[88:91], v166 offset0:4 offset1:6
	ds_read2_b64 v[92:95], v167 offset0:68 offset1:70
	v_cvt_pk_bf16_f32 v96, v96, v97
	v_cvt_pk_bf16_f32 v97, v98, v99
	v_cvt_pk_bf16_f32 v98, v100, v101
	v_cvt_pk_bf16_f32 v99, v102, v103
	s_setprio 1
	s_waitcnt lgkmcnt(7)
	v_mfma_f32_32x32x16_bf16 v[64:79], v[130:133], v[96:99], v[64:79]
	s_waitcnt lgkmcnt(6)
	v_mfma_f32_32x32x16_bf16 v[48:63], v[134:137], v[96:99], v[48:63]
	s_waitcnt lgkmcnt(5)
	v_mfma_f32_32x32x16_bf16 v[32:47], v[138:141], v[96:99], v[32:47]
	s_waitcnt lgkmcnt(4)
	v_mfma_f32_32x32x16_bf16 v[16:31], v[142:145], v[96:99], v[16:31]
	s_setprio 0
	ds_read2_b64 v[96:99], v164 offset0:136 offset1:138
	ds_read2_b64 v[100:103], v165 offset0:200 offset1:202
	ds_read2_b64 v[104:107], v166 offset0:8 offset1:10
	ds_read2_b64 v[108:111], v167 offset0:72 offset1:74
	v_cvt_pk_bf16_f32 v114, v115, v114
	v_cvt_pk_bf16_f32 v115, v116, v117
	v_cvt_pk_bf16_f32 v116, v118, v119
	v_cvt_pk_bf16_f32 v117, v120, v121
	s_setprio 1
	s_waitcnt lgkmcnt(7)
	v_mfma_f32_32x32x16_bf16 v[64:79], v[80:83], v[114:117], v[64:79]
	s_waitcnt lgkmcnt(6)
	v_mfma_f32_32x32x16_bf16 v[48:63], v[84:87], v[114:117], v[48:63]
	s_waitcnt lgkmcnt(5)
	v_mfma_f32_32x32x16_bf16 v[32:47], v[88:91], v[114:117], v[32:47]
	s_waitcnt lgkmcnt(4)
	v_mfma_f32_32x32x16_bf16 v[16:31], v[92:95], v[114:117], v[16:31]
	s_setprio 0
	ds_read2_b64 v[80:83], v164 offset0:140 offset1:142
	ds_read2_b64 v[84:87], v165 offset0:204 offset1:206
	ds_read2_b64 v[88:91], v166 offset0:12 offset1:14
	ds_read2_b64 v[92:95], v167 offset0:76 offset1:78
	v_cvt_pk_bf16_f32 v114, v122, v123
	v_cvt_pk_bf16_f32 v115, v124, v125
	v_cvt_pk_bf16_f32 v116, v126, v127
	v_cvt_pk_bf16_f32 v117, v128, v129
	s_setprio 1
	s_waitcnt lgkmcnt(7)
	v_mfma_f32_32x32x16_bf16 v[64:79], v[96:99], v[114:117], v[64:79]
	s_waitcnt lgkmcnt(6)
	v_mfma_f32_32x32x16_bf16 v[48:63], v[100:103], v[114:117], v[48:63]
	s_waitcnt lgkmcnt(5)
	v_mfma_f32_32x32x16_bf16 v[32:47], v[104:107], v[114:117], v[32:47]
	s_waitcnt lgkmcnt(4)
	v_mfma_f32_32x32x16_bf16 v[16:31], v[108:111], v[114:117], v[16:31]
	s_setprio 0
	v_cvt_pk_bf16_f32 v96, v146, v147
	v_cvt_pk_bf16_f32 v97, v148, v149
	v_cvt_pk_bf16_f32 v98, v150, v151
	v_cvt_pk_bf16_f32 v99, v152, v153
	s_setprio 1
	s_waitcnt lgkmcnt(3)
	v_mfma_f32_32x32x16_bf16 v[64:79], v[80:83], v[96:99], v[64:79]
	s_waitcnt lgkmcnt(2)
	v_mfma_f32_32x32x16_bf16 v[48:63], v[84:87], v[96:99], v[48:63]
	s_waitcnt lgkmcnt(1)
	v_mfma_f32_32x32x16_bf16 v[32:47], v[88:91], v[96:99], v[32:47]
	s_waitcnt lgkmcnt(0)
	v_mfma_f32_32x32x16_bf16 v[16:31], v[92:95], v[96:99], v[16:31]
	s_setprio 0
	v_mov_b32_e32 v80, v192
	s_barrier
	v_ashrrev_i32_e32 v81, 6, v177
	v_lshlrev_b32_e32 v80, 2, v80
	v_bitop3_b32 v80, v80, s33, v203 bitop3:0x6c
	ds_bpermute_b32 v80, v80, v154
	s_waitcnt lgkmcnt(0)
	v_add_f32_e32 v80, v154, v80
	v_div_scale_f32 v82, s[0:1], v80, v80, 1.0
	v_rcp_f32_e32 v83, v82
	v_div_scale_f32 v84, vcc, 1.0, v80, 1.0
	v_fma_f32 v85, -v82, v83, 1.0
	v_fmac_f32_e32 v83, v85, v83
	v_mul_f32_e32 v85, v84, v83
	v_fma_f32 v86, -v82, v85, v84
	v_fmac_f32_e32 v85, v86, v83
	v_fma_f32 v82, -v82, v85, v84
	v_div_fmas_f32 v82, v82, v83, v85
	v_div_fixup_f32 v84, v82, v80, 1.0
	v_cmp_lt_i32_e32 vcc, 3, v81
	v_lshlrev_b32_e32 v80, 2, v175
	s_and_saveexec_b64 s[20:21], vcc
	s_cbranch_execz .LBB0_749
	v_lshlrev_b32_e32 v82, 14, v81
	v_add3_u32 v82, 0, v80, v82
	v_add_u32_e32 v83, 0xffff0000, v82
	v_mul_f32_e32 v85, v64, v84
	ds_write_b32 v83, v85
	v_mul_f32_e32 v83, v65, v84
	v_add_u32_e32 v85, 0xffff0100, v82
	ds_write_b32 v85, v83
	v_mul_f32_e32 v83, v66, v84
	v_add_u32_e32 v85, 0xffff0200, v82
	ds_write_b32 v85, v83
	v_mul_f32_e32 v83, v67, v84
	v_add_u32_e32 v85, 0xffff0300, v82
	ds_write_b32 v85, v83
	v_mul_f32_e32 v83, v68, v84
	v_add_u32_e32 v85, 0xffff0400, v82
	ds_write_b32 v85, v83
	v_mul_f32_e32 v83, v69, v84
	v_add_u32_e32 v85, 0xffff0500, v82
	ds_write_b32 v85, v83
	v_mul_f32_e32 v83, v70, v84
	v_add_u32_e32 v85, 0xffff0600, v82
	ds_write_b32 v85, v83
	v_mul_f32_e32 v83, v71, v84
	v_add_u32_e32 v85, 0xffff0700, v82
	ds_write_b32 v85, v83
	v_mul_f32_e32 v83, v72, v84
	v_add_u32_e32 v85, 0xffff0800, v82
	ds_write_b32 v85, v83
	v_mul_f32_e32 v83, v73, v84
	v_add_u32_e32 v85, 0xffff0900, v82
	ds_write_b32 v85, v83
	v_mul_f32_e32 v83, v74, v84
	v_add_u32_e32 v85, 0xffff0a00, v82
	ds_write_b32 v85, v83
	v_mul_f32_e32 v83, v75, v84
	v_add_u32_e32 v85, 0xffff0b00, v82
	ds_write_b32 v85, v83
	v_mul_f32_e32 v83, v76, v84
	v_add_u32_e32 v85, 0xffff0c00, v82
	ds_write_b32 v85, v83
	v_mul_f32_e32 v83, v77, v84
	v_add_u32_e32 v85, 0xffff0d00, v82
	ds_write_b32 v85, v83
	v_mul_f32_e32 v83, v78, v84
	v_add_u32_e32 v85, 0xffff0e00, v82
	ds_write_b32 v85, v83
	v_mul_f32_e32 v83, v79, v84
	v_add_u32_e32 v85, 0xffff0f00, v82
	ds_write_b32 v85, v83
	v_add_u32_e32 v83, 0xffff1000, v82
	v_mul_f32_e32 v85, v48, v84
	ds_write_b32 v83, v85
	v_mul_f32_e32 v83, v49, v84
	v_add_u32_e32 v85, 0xffff1100, v82
	ds_write_b32 v85, v83
	v_mul_f32_e32 v83, v50, v84
	v_add_u32_e32 v85, 0xffff1200, v82
	ds_write_b32 v85, v83
	v_mul_f32_e32 v83, v51, v84
	v_add_u32_e32 v85, 0xffff1300, v82
	ds_write_b32 v85, v83
	v_mul_f32_e32 v83, v52, v84
	v_add_u32_e32 v85, 0xffff1400, v82
	ds_write_b32 v85, v83
	v_mul_f32_e32 v83, v53, v84
	v_add_u32_e32 v85, 0xffff1500, v82
	ds_write_b32 v85, v83
	v_mul_f32_e32 v83, v54, v84
	v_add_u32_e32 v85, 0xffff1600, v82
	ds_write_b32 v85, v83
	v_mul_f32_e32 v83, v55, v84
	v_add_u32_e32 v85, 0xffff1700, v82
	ds_write_b32 v85, v83
	v_mul_f32_e32 v83, v56, v84
	v_add_u32_e32 v85, 0xffff1800, v82
	ds_write_b32 v85, v83
	v_mul_f32_e32 v83, v57, v84
	v_add_u32_e32 v85, 0xffff1900, v82
	ds_write_b32 v85, v83
	v_mul_f32_e32 v83, v58, v84
	v_add_u32_e32 v85, 0xffff1a00, v82
	ds_write_b32 v85, v83
	v_mul_f32_e32 v83, v59, v84
	v_add_u32_e32 v85, 0xffff1b00, v82
	ds_write_b32 v85, v83
	v_mul_f32_e32 v83, v60, v84
	v_add_u32_e32 v85, 0xffff1c00, v82
	ds_write_b32 v85, v83
	v_mul_f32_e32 v83, v61, v84
	v_add_u32_e32 v85, 0xffff1d00, v82
	ds_write_b32 v85, v83
	v_mul_f32_e32 v83, v62, v84
	v_add_u32_e32 v85, 0xffff1e00, v82
	ds_write_b32 v85, v83
	v_mul_f32_e32 v83, v63, v84
	v_add_u32_e32 v85, 0xffff1f00, v82
	ds_write_b32 v85, v83
	v_add_u32_e32 v83, 0xffff2000, v82
	v_mul_f32_e32 v85, v32, v84
	ds_write_b32 v83, v85
	v_mul_f32_e32 v83, v33, v84
	v_add_u32_e32 v85, 0xffff2100, v82
	ds_write_b32 v85, v83
	v_mul_f32_e32 v83, v34, v84
	v_add_u32_e32 v85, 0xffff2200, v82
	ds_write_b32 v85, v83
	v_mul_f32_e32 v83, v35, v84
	v_add_u32_e32 v85, 0xffff2300, v82
	ds_write_b32 v85, v83
	v_mul_f32_e32 v83, v36, v84
	v_add_u32_e32 v85, 0xffff2400, v82
	ds_write_b32 v85, v83
	v_mul_f32_e32 v83, v37, v84
	v_add_u32_e32 v85, 0xffff2500, v82
	ds_write_b32 v85, v83
	v_mul_f32_e32 v83, v38, v84
	v_add_u32_e32 v85, 0xffff2600, v82
	ds_write_b32 v85, v83
	v_mul_f32_e32 v83, v39, v84
	v_add_u32_e32 v85, 0xffff2700, v82
	ds_write_b32 v85, v83
	v_mul_f32_e32 v83, v40, v84
	v_add_u32_e32 v85, 0xffff2800, v82
	ds_write_b32 v85, v83
	v_mul_f32_e32 v83, v41, v84
	v_add_u32_e32 v85, 0xffff2900, v82
	ds_write_b32 v85, v83
	v_mul_f32_e32 v83, v42, v84
	v_add_u32_e32 v85, 0xffff2a00, v82
	ds_write_b32 v85, v83
	v_mul_f32_e32 v83, v43, v84
	v_add_u32_e32 v85, 0xffff2b00, v82
	ds_write_b32 v85, v83
	v_mul_f32_e32 v83, v44, v84
	v_add_u32_e32 v85, 0xffff2c00, v82
	ds_write_b32 v85, v83
	v_mul_f32_e32 v83, v45, v84
	v_add_u32_e32 v85, 0xffff2d00, v82
	ds_write_b32 v85, v83
	v_mul_f32_e32 v83, v46, v84
	v_add_u32_e32 v85, 0xffff2e00, v82
	ds_write_b32 v85, v83
	v_mul_f32_e32 v83, v47, v84
	v_add_u32_e32 v85, 0xffff2f00, v82
	ds_write_b32 v85, v83
	v_add_u32_e32 v83, 0xffff3000, v82
	v_mul_f32_e32 v85, v16, v84
	ds_write_b32 v83, v85
	v_mul_f32_e32 v83, v17, v84
	v_add_u32_e32 v85, 0xffff3100, v82
	ds_write_b32 v85, v83
	v_mul_f32_e32 v83, v18, v84
	v_add_u32_e32 v85, 0xffff3200, v82
	ds_write_b32 v85, v83
	v_mul_f32_e32 v83, v19, v84
	v_add_u32_e32 v85, 0xffff3300, v82
	ds_write_b32 v85, v83
	v_mul_f32_e32 v83, v20, v84
	v_add_u32_e32 v85, 0xffff3400, v82
	ds_write_b32 v85, v83
	v_mul_f32_e32 v83, v21, v84
	v_add_u32_e32 v85, 0xffff3500, v82
	ds_write_b32 v85, v83
	v_mul_f32_e32 v83, v22, v84
	v_add_u32_e32 v85, 0xffff3600, v82
	ds_write_b32 v85, v83
	v_mul_f32_e32 v83, v23, v84
	v_add_u32_e32 v85, 0xffff3700, v82
	ds_write_b32 v85, v83
	v_mul_f32_e32 v83, v24, v84
	v_add_u32_e32 v85, 0xffff3800, v82
	ds_write_b32 v85, v83
	v_mul_f32_e32 v83, v25, v84
	v_add_u32_e32 v85, 0xffff3900, v82
	ds_write_b32 v85, v83
	v_mul_f32_e32 v83, v26, v84
	v_add_u32_e32 v85, 0xffff3a00, v82
	ds_write_b32 v85, v83
	v_mul_f32_e32 v83, v27, v84
	v_add_u32_e32 v85, 0xffff3b00, v82
	ds_write_b32 v85, v83
	v_mul_f32_e32 v83, v28, v84
	v_add_u32_e32 v85, 0xffff3c00, v82
	ds_write_b32 v85, v83
	v_mul_f32_e32 v83, v29, v84
	v_add_u32_e32 v85, 0xffff3d00, v82
	ds_write_b32 v85, v83
	v_mul_f32_e32 v83, v30, v84
	v_add_u32_e32 v85, 0xffff3e00, v82
	ds_write_b32 v85, v83
	v_mul_f32_e32 v83, v31, v84
	v_add_u32_e32 v82, 0xffff3f00, v82
	ds_write_b32 v82, v83

.LBB0_870:
	s_setprio 0
	v_mov_b32_e32 v50, v192
	v_readlane_b32 s0, v254, 37
	v_lshlrev_b32_e32 v50, 2, v50
	v_bitop3_b32 v50, v50, s33, v203 bitop3:0x6c
	ds_bpermute_b32 v50, v50, v134
	v_lshlrev_b64 v[48:49], 11, v[118:119]
	v_readlane_b32 s1, v254, 38
	s_waitcnt lgkmcnt(0)
	v_add_f32_e32 v50, v134, v50
	v_lshl_add_u64 v[48:49], s[0:1], 0, v[48:49]
	v_div_scale_f32 v51, s[0:1], v50, v50, 1.0
	v_rcp_f32_e32 v52, v51
	v_lshl_add_u64 v[48:49], v[120:121], 1, v[48:49]
	v_fma_f32 v53, -v51, v52, 1.0
	v_fmac_f32_e32 v52, v53, v52
	v_div_scale_f32 v53, vcc, 1.0, v50, 1.0
	v_mul_f32_e32 v54, v53, v52
	v_fma_f32 v55, -v51, v54, v53
	v_fmac_f32_e32 v54, v55, v52
	v_fma_f32 v51, -v51, v54, v53
	v_div_fmas_f32 v51, v51, v52, v54
	v_div_fixup_f32 v50, v51, v50, 1.0
	v_lshlrev_b32_e32 v52, 11, v123
	v_mov_b32_e32 v53, v112
	v_lshl_add_u64 v[48:49], v[48:49], 0, v[52:53]
	v_mov_b32_e32 v123, v112
	v_pk_mul_f32 v[32:33], v[32:33], v[50:51] op_sel_hi:[1,0]
	v_pk_mul_f32 v[34:35], v[34:35], v[50:51] op_sel_hi:[1,0]
	v_pk_mul_f32 v[16:17], v[16:17], v[50:51] op_sel_hi:[1,0]
	v_pk_mul_f32 v[18:19], v[18:19], v[50:51] op_sel_hi:[1,0]
	v_lshl_add_u64 v[48:49], v[48:49], 0, v[122:123]
	v_cvt_pk_bf16_f32 v32, v32, v33
	v_cvt_pk_bf16_f32 v33, v34, v35
	v_cvt_pk_bf16_f32 v16, v16, v17
	v_cvt_pk_bf16_f32 v17, v18, v19
	global_store_dwordx2 v[48:49], v[32:33], off
	v_pk_mul_f32 v[32:33], v[36:37], v[50:51] op_sel_hi:[1,0]
	v_pk_mul_f32 v[34:35], v[38:39], v[50:51] op_sel_hi:[1,0]
	global_store_dwordx2 v[48:49], v[16:17], off offset:64
	v_pk_mul_f32 v[16:17], v[20:21], v[50:51] op_sel_hi:[1,0]
	v_pk_mul_f32 v[18:19], v[22:23], v[50:51] op_sel_hi:[1,0]
	v_cvt_pk_bf16_f32 v32, v32, v33
	v_cvt_pk_bf16_f32 v33, v34, v35
	v_cvt_pk_bf16_f32 v16, v16, v17
	v_cvt_pk_bf16_f32 v17, v18, v19
	global_store_dwordx2 v[48:49], v[32:33], off offset:16
	v_pk_mul_f32 v[32:33], v[40:41], v[50:51] op_sel_hi:[1,0]
	v_pk_mul_f32 v[34:35], v[42:43], v[50:51] op_sel_hi:[1,0]
	global_store_dwordx2 v[48:49], v[16:17], off offset:80
	v_pk_mul_f32 v[16:17], v[24:25], v[50:51] op_sel_hi:[1,0]
	v_pk_mul_f32 v[18:19], v[26:27], v[50:51] op_sel_hi:[1,0]
	v_cvt_pk_bf16_f32 v32, v32, v33
	v_cvt_pk_bf16_f32 v33, v34, v35
	v_cvt_pk_bf16_f32 v16, v16, v17
	v_cvt_pk_bf16_f32 v17, v18, v19
	global_store_dwordx2 v[48:49], v[32:33], off offset:32
	v_pk_mul_f32 v[32:33], v[44:45], v[50:51] op_sel_hi:[1,0]
	v_pk_mul_f32 v[34:35], v[46:47], v[50:51] op_sel_hi:[1,0]
	global_store_dwordx2 v[48:49], v[16:17], off offset:96
	v_pk_mul_f32 v[16:17], v[28:29], v[50:51] op_sel_hi:[1,0]
	v_pk_mul_f32 v[18:19], v[30:31], v[50:51] op_sel_hi:[1,0]
	v_cvt_pk_bf16_f32 v32, v32, v33
	v_cvt_pk_bf16_f32 v33, v34, v35
	v_cvt_pk_bf16_f32 v16, v16, v17
	v_cvt_pk_bf16_f32 v17, v18, v19
	global_store_dwordx2 v[48:49], v[32:33], off offset:48
	global_store_dwordx2 v[48:49], v[16:17], off offset:112
	s_load_dword s0, s[68:69], 0x10
	s_waitcnt lgkmcnt(0)
	s_lshr_b32 s0, s0, 16
	s_cmp_lg_u32 s0, 0
	s_cselect_b64 s[0:1], -1, 0
	s_cmp_lg_u64 s[0:1], 0
	s_addc_u32 s4, s4, s88
	s_cmpk_gt_i32 s4, 0x3ff
	s_cbranch_scc1 .LBB0_888

.LBB0_876:
	v_mov_b32_e32 v64, v192
	v_mov_b32_e32 v39, v112
	v_and_b32_e32 v123, 31, v64
	v_bfe_u32 v52, v64, 5, 1
	v_mad_u64_u32 v[22:23], s[0:1], v123, s24, v[20:21]
	v_lshlrev_b32_e32 v20, 4, v52
	v_mov_b32_e32 v21, v112
	v_lshl_add_u64 v[42:43], v[22:23], 0, v[20:21]
	v_ashrrev_i32_e32 v21, 31, v64
	v_lshrrev_b32_e32 v21, 29, v21
	v_ashrrev_i32_e32 v65, 3, v64
	v_add_u32_e32 v21, v64, v21
	v_mad_i64_i32 v[34:35], s[0:1], s22, v65, 0
	v_ashrrev_i32_e32 v66, 3, v21
	v_and_b32_e32 v21, -8, v21
	v_lshl_add_u64 v[40:41], v[34:35], 1, v[16:17]
	v_sub_u32_e32 v21, v64, v21
	v_mad_i64_i32 v[34:35], s[0:1], s20, v66, 0
	v_lshlrev_b64 v[46:47], 1, v[34:35]
	v_lshlrev_b32_e32 v34, 3, v21
	global_load_dwordx4 v[22:25], v[42:43], off
	global_load_dwordx4 v[26:29], v[42:43], off offset:32
	global_load_dwordx4 v[30:33], v[42:43], off offset:64
	v_lshlrev_b32_e32 v36, 3, v64
	v_ashrrev_i32_e32 v35, 31, v34
	v_and_b32_e32 v53, 56, v36
	v_lshl_add_u64 v[36:37], v[18:19], 0, v[46:47]
	v_lshlrev_b64 v[48:49], 1, v[34:35]
	v_lshlrev_b32_e32 v38, 1, v53
	v_lshl_add_u64 v[34:35], v[36:37], 0, v[48:49]
	global_load_dwordx4 v[34:37], v[34:35], off
	v_lshl_add_u64 v[50:51], v[40:41], 0, v[38:39]
	global_load_dwordx4 v[38:41], v[50:51], off
	s_nop 0
	global_load_dwordx4 v[42:45], v[42:43], off offset:96
	s_movk_i32 s0, 0x48
	v_lshlrev_b32_e32 v122, 3, v52
	v_mul_lo_u32 v52, v65, s0
	v_add_lshl_u32 v67, v52, v53, 1
	v_mul_lo_u32 v52, v66, s71
	v_lshl_add_u32 v21, v21, 4, 0
	v_add_u32_e32 v132, v21, v52
	s_mov_b32 s6, 0x3e38aa3b
	s_lshl_b32 s0, s20, 7
	s_mov_b32 s1, s96
	v_add_u32_e32 v133, 0, v67
	v_lshl_add_u64 v[128:129], v[18:19], 0, v[48:49]
	v_add_u32_e32 v20, 0, v20
	v_mov_b32_e32 v113, v112
	v_mul_u32_u24_e32 v21, 0x90, v123
	v_mov_b32_e32 v114, v112
	v_mov_b32_e32 v115, v112
	v_mov_b32_e32 v134, 0
	s_waitcnt vmcnt(0)
	v_mov_b64_e32 v[104:105], v[112:113]
	v_mov_b64_e32 v[108:109], v[112:113]
	s_mov_b32 s24, 3
	v_add_u32_e32 v135, v20, v21
	v_mov_b64_e32 v[106:107], v[114:115]
	v_mov_b64_e32 v[110:111], v[114:115]
	s_waitcnt vmcnt(0)
	v_lshlrev_b32_e32 v52, 16, v22
	v_and_b32_e32 v53, 0xffff0000, v22
	v_lshlrev_b32_e32 v22, 16, v23
	v_and_b32_e32 v23, 0xffff0000, v23
	v_pk_mul_f32 v[22:23], v[22:23], s[6:7] op_sel_hi:[1,0]
	v_lshlrev_b32_e32 v62, 16, v32
	v_cvt_pk_bf16_f32 v81, v22, v23
	v_lshl_add_u64 v[22:23], v[18:19], 0, s[0:1]
	v_lshl_add_u64 v[22:23], v[22:23], 0, v[46:47]
	v_lshl_add_u64 v[22:23], v[22:23], 0, v[48:49]
	ds_write_b128 v132, v[34:37]
	ds_write_b128 v133, v[38:41] offset:9216
	s_waitcnt lgkmcnt(0)
	s_barrier
	global_load_dwordx4 v[96:99], v[22:23], off
	global_load_dwordx4 v[100:103], v[50:51], off offset:128
	v_and_b32_e32 v63, 0xffff0000, v32
	v_lshlrev_b32_e32 v32, 16, v33
	v_and_b32_e32 v33, 0xffff0000, v33
	v_pk_mul_f32 v[22:23], v[32:33], s[6:7] op_sel_hi:[1,0]
	v_lshlrev_b32_e32 v54, 16, v24
	v_cvt_pk_bf16_f32 v91, v22, v23
	v_lshlrev_b32_e32 v22, 16, v42
	v_and_b32_e32 v23, 0xffff0000, v42
	v_pk_mul_f32 v[22:23], v[22:23], s[6:7] op_sel_hi:[1,0]
	v_and_b32_e32 v55, 0xffff0000, v24
	v_cvt_pk_bf16_f32 v92, v22, v23
	v_lshlrev_b32_e32 v22, 16, v43
	v_and_b32_e32 v23, 0xffff0000, v43
	v_pk_mul_f32 v[22:23], v[22:23], s[6:7] op_sel_hi:[1,0]
	v_lshlrev_b32_e32 v24, 16, v25
	v_cvt_pk_bf16_f32 v93, v22, v23
	v_lshlrev_b32_e32 v22, 16, v44
	v_and_b32_e32 v23, 0xffff0000, v44
	v_pk_mul_f32 v[22:23], v[22:23], s[6:7] op_sel_hi:[1,0]
	v_and_b32_e32 v25, 0xffff0000, v25
	v_cvt_pk_bf16_f32 v94, v22, v23
	v_lshlrev_b32_e32 v22, 16, v45
	v_and_b32_e32 v23, 0xffff0000, v45
	v_pk_mul_f32 v[22:23], v[22:23], s[6:7] op_sel_hi:[1,0]
	v_pk_mul_f32 v[24:25], v[24:25], s[6:7] op_sel_hi:[1,0]
	v_cvt_pk_bf16_f32 v95, v22, v23
	v_lshlrev_b32_e32 v23, 1, v66
	v_cvt_pk_bf16_f32 v83, v24, v25
	v_add_u32_e32 v24, 0x180, v23
	v_mad_i64_i32 v[124:125], s[0:1], s20, v24, 0
	v_and_b32_e32 v18, 7, v64
	s_lshl_b32 s0, s22, 1
	v_lshlrev_b32_e32 v18, 4, v18
	v_mov_b32_e32 v19, v112
	v_mad_i64_i32 v[18:19], s[0:1], s0, v65, v[18:19]
	v_lshlrev_b32_e32 v56, 16, v26
	v_and_b32_e32 v57, 0xffff0000, v26
	v_lshlrev_b32_e32 v26, 16, v27
	v_and_b32_e32 v27, 0xffff0000, v27
	v_lshlrev_b32_e32 v58, 16, v28
	v_and_b32_e32 v59, 0xffff0000, v28
	v_lshlrev_b32_e32 v28, 16, v29
	v_and_b32_e32 v29, 0xffff0000, v29
	v_lshlrev_b32_e32 v60, 16, v30
	v_and_b32_e32 v61, 0xffff0000, v30
	v_lshlrev_b32_e32 v30, 16, v31
	v_and_b32_e32 v31, 0xffff0000, v31
	v_lshl_add_u64 v[16:17], v[16:17], 0, v[18:19]
	s_mov_b64 s[0:1], 0x100
	v_pk_mul_f32 v[52:53], v[52:53], s[6:7] op_sel_hi:[1,0]
	v_pk_mul_f32 v[54:55], v[54:55], s[6:7] op_sel_hi:[1,0]
	v_pk_mul_f32 v[56:57], v[56:57], s[6:7] op_sel_hi:[1,0]
	v_pk_mul_f32 v[26:27], v[26:27], s[6:7] op_sel_hi:[1,0]
	v_pk_mul_f32 v[58:59], v[58:59], s[6:7] op_sel_hi:[1,0]
	v_pk_mul_f32 v[28:29], v[28:29], s[6:7] op_sel_hi:[1,0]
	v_pk_mul_f32 v[60:61], v[60:61], s[6:7] op_sel_hi:[1,0]
	v_pk_mul_f32 v[30:31], v[30:31], s[6:7] op_sel_hi:[1,0]
	v_pk_mul_f32 v[62:63], v[62:63], s[6:7] op_sel_hi:[1,0]
	v_sub_u32_e32 v22, v20, v122
	v_lshl_add_u64 v[130:131], v[16:17], 0, s[0:1]
	v_add_u32_e32 v16, 0x100, v23
	v_cvt_pk_bf16_f32 v80, v52, v53
	v_cvt_pk_bf16_f32 v82, v54, v55
	v_cvt_pk_bf16_f32 v84, v56, v57
	v_cvt_pk_bf16_f32 v85, v26, v27
	v_cvt_pk_bf16_f32 v86, v58, v59
	v_cvt_pk_bf16_f32 v87, v28, v29
	v_cvt_pk_bf16_f32 v88, v60, v61
	v_cvt_pk_bf16_f32 v89, v30, v31
	v_cvt_pk_bf16_f32 v90, v62, v63
	s_lshl_b32 s6, s20, 8
	s_mov_b32 s7, s96
	v_mad_i64_i32 v[126:127], s[0:1], s20, v16, 0
	v_add_u32_e32 v136, v22, v21
	v_mov_b32_e32 v16, 0
	v_mov_b32_e32 v17, v134
	v_mov_b32_e32 v18, v134
	v_mov_b32_e32 v19, v134
	v_mov_b32_e32 v20, v134
	v_mov_b32_e32 v21, v134
	v_mov_b32_e32 v22, v134
	v_mov_b32_e32 v23, v134
	v_mov_b32_e32 v24, v134
	v_mov_b32_e32 v25, v134
	v_mov_b32_e32 v26, v134
	v_mov_b32_e32 v27, v134
	v_mov_b32_e32 v28, v134
	v_mov_b32_e32 v29, v134
	v_mov_b32_e32 v30, v134
	v_mov_b32_e32 v31, v134
	v_mov_b32_e32 v32, 0
	v_mov_b32_e32 v33, v134
	v_mov_b32_e32 v34, v134
	v_mov_b32_e32 v35, v134
	v_mov_b32_e32 v36, v134
	v_mov_b32_e32 v37, v134
	v_mov_b32_e32 v38, v134
	v_mov_b32_e32 v39, v134
	v_mov_b32_e32 v40, v134
	v_mov_b32_e32 v41, v134
	v_mov_b32_e32 v42, v134
	v_mov_b32_e32 v43, v134
	v_mov_b32_e32 v44, v134
	v_mov_b32_e32 v45, v134
	v_mov_b32_e32 v46, v134
	v_mov_b32_e32 v47, v134
	v_readfirstlane_b32 s25, v192
	s_nop 0
	s_cmp_ge_u32 s25, 0x100
	s_cbranch_scc0 .Lattn_prio_skip
	s_setprio 1
.Lattn_prio_skip:
	s_branch .LBB0_878
.LBB0_877:
	v_add_f32_e32 v64, 0, v64
	v_add_f32_e32 v64, v65, v64
	v_add_f32_e32 v64, v66, v64
	v_add_f32_e32 v64, v67, v64
	v_add_f32_e32 v64, v68, v64
	v_add_f32_e32 v64, v69, v64
	v_add_f32_e32 v64, v70, v64
	v_add_f32_e32 v64, v71, v64
	v_add_f32_e32 v64, v72, v64
	v_add_f32_e32 v64, v73, v64
	v_add_f32_e32 v64, v74, v64
	v_add_f32_e32 v64, v75, v64
	v_add_f32_e32 v64, v76, v64
	v_add_f32_e32 v64, v77, v64
	v_add_f32_e32 v64, v78, v64
	v_add_f32_e32 v64, v79, v64
	v_add_f32_e32 v48, v48, v64
	v_add_f32_e32 v48, v49, v48
	v_add_f32_e32 v48, v50, v48
	v_add_f32_e32 v48, v51, v48
	v_add_f32_e32 v48, v52, v48
	v_add_f32_e32 v48, v53, v48
	v_add_f32_e32 v48, v54, v48
	v_add_f32_e32 v48, v55, v48
	v_add_f32_e32 v48, v56, v48
	v_add_f32_e32 v48, v57, v48
	v_add_f32_e32 v48, v58, v48
	v_add_f32_e32 v48, v59, v48
	v_add_f32_e32 v48, v60, v48
	v_add_f32_e32 v48, v61, v48
	v_add_f32_e32 v48, v62, v48
	s_add_i32 s24, s24, 2
	v_add_f32_e32 v48, v63, v48
	s_mov_b64 s[0:1], 0x100
	s_cmp_ge_u32 s25, s5
	v_add_f32_e32 v134, v134, v48
	v_lshl_add_u64 v[128:129], v[128:129], 0, s[6:7]
	v_lshl_add_u64 v[130:131], v[130:131], 0, s[0:1]
	s_cselect_b64 s[22:23], -1, 0
	s_waitcnt lgkmcnt(0)
	s_barrier
	s_and_b64 vcc, exec, s[22:23]
	s_cbranch_vccnz .LBB0_870

.LBB0_880:
	ds_read_b128 v[48:51], v135
	ds_read_b128 v[138:141], v135 offset:32
	ds_read_b128 v[142:145], v135 offset:64
	ds_read_b128 v[146:149], v135 offset:96
	ds_read_b128 v[150:153], v135 offset:4608
	ds_read_b128 v[154:157], v135 offset:4640
	ds_read_b128 v[158:161], v135 offset:4672
	ds_read_b128 v[170:173], v135 offset:4704
	v_add_u32_e32 v113, 0x2000, v136
	v_add_u32_e32 v114, 0x3000, v136
	ds_read2_b64 v[174:177], v113 offset0:128 offset1:130
	ds_read2_b64 v[178:181], v114 offset0:192 offset1:194
	s_waitcnt lgkmcnt(9)
	v_mfma_f32_32x32x16_bf16 v[64:79], v[48:51], v[80:83], v[0:15]
	s_waitcnt lgkmcnt(5)
	v_mfma_f32_32x32x16_bf16 v[48:63], v[150:153], v[80:83], v[0:15]
	v_mfma_f32_32x32x16_bf16 v[64:79], v[138:141], v[84:87], v[64:79]
	s_waitcnt lgkmcnt(4)
	v_mfma_f32_32x32x16_bf16 v[48:63], v[154:157], v[84:87], v[48:63]
	v_mfma_f32_32x32x16_bf16 v[64:79], v[142:145], v[88:91], v[64:79]
	s_waitcnt lgkmcnt(3)
	v_mfma_f32_32x32x16_bf16 v[48:63], v[158:161], v[88:91], v[48:63]
	v_mfma_f32_32x32x16_bf16 v[64:79], v[146:149], v[92:95], v[64:79]
	s_waitcnt lgkmcnt(2)
	v_mfma_f32_32x32x16_bf16 v[48:63], v[170:173], v[92:95], v[48:63]
	ds_read2_b64 v[138:141], v113 offset0:132 offset1:134
	ds_read2_b64 v[142:145], v114 offset0:196 offset1:198
	s_nop 6
	v_exp_f32_e32 v64, v64
	v_exp_f32_e32 v65, v65
	v_exp_f32_e32 v66, v66
	v_exp_f32_e32 v67, v67
	v_exp_f32_e32 v68, v68
	v_exp_f32_e32 v69, v69
	v_exp_f32_e32 v70, v70
	v_exp_f32_e32 v71, v71
	v_exp_f32_e32 v72, v72
	v_exp_f32_e32 v73, v73
	v_exp_f32_e32 v74, v74
	v_exp_f32_e32 v75, v75
	v_exp_f32_e32 v76, v76
	v_exp_f32_e32 v77, v77
	v_exp_f32_e32 v78, v78
	v_exp_f32_e32 v79, v79
	v_exp_f32_e32 v48, v48
	v_exp_f32_e32 v49, v49
	v_exp_f32_e32 v50, v50
	v_exp_f32_e32 v51, v51
	v_exp_f32_e32 v52, v52
	v_exp_f32_e32 v53, v53
	v_exp_f32_e32 v54, v54
	v_exp_f32_e32 v55, v55
	v_exp_f32_e32 v56, v56
	v_exp_f32_e32 v57, v57
	v_exp_f32_e32 v58, v58
	v_exp_f32_e32 v59, v59
	v_exp_f32_e32 v60, v60
	v_exp_f32_e32 v61, v61
	v_exp_f32_e32 v62, v62
	v_exp_f32_e32 v63, v63
	v_cvt_pk_bf16_f32 v146, v64, v65
	v_cvt_pk_bf16_f32 v147, v66, v67
	v_cvt_pk_bf16_f32 v148, v68, v69
	v_cvt_pk_bf16_f32 v149, v70, v71
	s_waitcnt lgkmcnt(3)
	v_mfma_f32_32x32x16_bf16 v[32:47], v[174:177], v[146:149], v[32:47]
	s_waitcnt lgkmcnt(2)
	v_mfma_f32_32x32x16_bf16 v[16:31], v[178:181], v[146:149], v[16:31]
	ds_read2_b64 v[146:149], v113 offset0:136 offset1:138
	ds_read2_b64 v[150:153], v114 offset0:200 offset1:202
	v_cvt_pk_bf16_f32 v154, v72, v73
	v_cvt_pk_bf16_f32 v155, v74, v75
	v_cvt_pk_bf16_f32 v156, v76, v77
	v_cvt_pk_bf16_f32 v157, v78, v79
	s_waitcnt lgkmcnt(3)
	v_mfma_f32_32x32x16_bf16 v[32:47], v[138:141], v[154:157], v[32:47]
	s_waitcnt lgkmcnt(2)
	v_mfma_f32_32x32x16_bf16 v[16:31], v[142:145], v[154:157], v[16:31]
	ds_read2_b64 v[138:141], v113 offset0:140 offset1:142
	ds_read2_b64 v[142:145], v114 offset0:204 offset1:206
	v_cvt_pk_bf16_f32 v154, v48, v49
	v_cvt_pk_bf16_f32 v155, v50, v51
	v_cvt_pk_bf16_f32 v156, v52, v53
	v_cvt_pk_bf16_f32 v157, v54, v55
	s_waitcnt lgkmcnt(3)
	v_mfma_f32_32x32x16_bf16 v[32:47], v[146:149], v[154:157], v[32:47]
	s_waitcnt lgkmcnt(2)
	v_mfma_f32_32x32x16_bf16 v[16:31], v[150:153], v[154:157], v[16:31]
	v_cvt_pk_bf16_f32 v146, v56, v57
	v_cvt_pk_bf16_f32 v147, v58, v59
	v_cvt_pk_bf16_f32 v148, v60, v61
	v_cvt_pk_bf16_f32 v149, v62, v63
	s_waitcnt lgkmcnt(1)
	v_mfma_f32_32x32x16_bf16 v[32:47], v[138:141], v[146:149], v[32:47]
	s_waitcnt lgkmcnt(0)
	v_mfma_f32_32x32x16_bf16 v[16:31], v[142:145], v[146:149], v[16:31]
	s_add_i32 s22, s24, -2
	s_cmp_lt_u32 s22, s5
	s_cselect_b64 s[0:1], -1, 0
	s_cmp_ge_u32 s22, s5
	s_cbranch_scc1 .LBB0_882
	s_waitcnt vmcnt(1)
	ds_write_b128 v132, v[96:99] offset:18432
	s_waitcnt vmcnt(0)
	ds_write_b128 v133, v[100:103] offset:27648

.LBB0_885:
	ds_read_b128 v[48:51], v135 offset:18432
	ds_read_b128 v[138:141], v135 offset:18464
	ds_read_b128 v[142:145], v135 offset:18496
	ds_read_b128 v[146:149], v135 offset:18528
	ds_read_b128 v[150:153], v135 offset:23040
	ds_read_b128 v[154:157], v135 offset:23072
	ds_read_b128 v[158:161], v135 offset:23104
	ds_read_b128 v[170:173], v135 offset:23136
	v_add_u32_e32 v113, 0x6800, v136
	v_add_u32_e32 v114, 0x7800, v136
	ds_read2_b64 v[174:177], v113 offset0:128 offset1:130
	ds_read2_b64 v[178:181], v114 offset0:192 offset1:194
	s_waitcnt lgkmcnt(9)
	v_mfma_f32_32x32x16_bf16 v[64:79], v[48:51], v[80:83], v[0:15]
	s_waitcnt lgkmcnt(5)
	v_mfma_f32_32x32x16_bf16 v[48:63], v[150:153], v[80:83], v[0:15]
	v_mfma_f32_32x32x16_bf16 v[64:79], v[138:141], v[84:87], v[64:79]
	s_waitcnt lgkmcnt(4)
	v_mfma_f32_32x32x16_bf16 v[48:63], v[154:157], v[84:87], v[48:63]
	v_mfma_f32_32x32x16_bf16 v[64:79], v[142:145], v[88:91], v[64:79]
	s_waitcnt lgkmcnt(3)
	v_mfma_f32_32x32x16_bf16 v[48:63], v[158:161], v[88:91], v[48:63]
	v_mfma_f32_32x32x16_bf16 v[64:79], v[146:149], v[92:95], v[64:79]
	s_waitcnt lgkmcnt(2)
	v_mfma_f32_32x32x16_bf16 v[48:63], v[170:173], v[92:95], v[48:63]
	ds_read2_b64 v[138:141], v113 offset0:132 offset1:134
	ds_read2_b64 v[142:145], v114 offset0:196 offset1:198
	s_nop 6
	v_exp_f32_e32 v64, v64
	v_exp_f32_e32 v65, v65
	v_exp_f32_e32 v66, v66
	v_exp_f32_e32 v67, v67
	v_exp_f32_e32 v68, v68
	v_exp_f32_e32 v69, v69
	v_exp_f32_e32 v70, v70
	v_exp_f32_e32 v71, v71
	v_exp_f32_e32 v72, v72
	v_exp_f32_e32 v73, v73
	v_exp_f32_e32 v74, v74
	v_exp_f32_e32 v75, v75
	v_exp_f32_e32 v76, v76
	v_exp_f32_e32 v77, v77
	v_exp_f32_e32 v78, v78
	v_exp_f32_e32 v79, v79
	v_exp_f32_e32 v48, v48
	v_exp_f32_e32 v49, v49
	v_exp_f32_e32 v50, v50
	v_exp_f32_e32 v51, v51
	v_exp_f32_e32 v52, v52
	v_exp_f32_e32 v53, v53
	v_exp_f32_e32 v54, v54
	v_exp_f32_e32 v55, v55
	v_exp_f32_e32 v56, v56
	v_exp_f32_e32 v57, v57
	v_exp_f32_e32 v58, v58
	v_exp_f32_e32 v59, v59
	v_exp_f32_e32 v60, v60
	v_exp_f32_e32 v61, v61
	v_exp_f32_e32 v62, v62
	v_exp_f32_e32 v63, v63
	v_cvt_pk_bf16_f32 v146, v64, v65
	v_cvt_pk_bf16_f32 v147, v66, v67
	v_cvt_pk_bf16_f32 v148, v68, v69
	v_cvt_pk_bf16_f32 v149, v70, v71
	s_waitcnt lgkmcnt(3)
	v_mfma_f32_32x32x16_bf16 v[32:47], v[174:177], v[146:149], v[32:47]
	s_waitcnt lgkmcnt(2)
	v_mfma_f32_32x32x16_bf16 v[16:31], v[178:181], v[146:149], v[16:31]
	ds_read2_b64 v[146:149], v113 offset0:136 offset1:138
	ds_read2_b64 v[150:153], v114 offset0:200 offset1:202
	v_cvt_pk_bf16_f32 v154, v72, v73
	v_cvt_pk_bf16_f32 v155, v74, v75
	v_cvt_pk_bf16_f32 v156, v76, v77
	v_cvt_pk_bf16_f32 v157, v78, v79
	s_waitcnt lgkmcnt(3)
	v_mfma_f32_32x32x16_bf16 v[32:47], v[138:141], v[154:157], v[32:47]
	s_waitcnt lgkmcnt(2)
	v_mfma_f32_32x32x16_bf16 v[16:31], v[142:145], v[154:157], v[16:31]
	ds_read2_b64 v[138:141], v113 offset0:140 offset1:142
	ds_read2_b64 v[142:145], v114 offset0:204 offset1:206
	v_cvt_pk_bf16_f32 v154, v48, v49
	v_cvt_pk_bf16_f32 v155, v50, v51
	v_cvt_pk_bf16_f32 v156, v52, v53
	v_cvt_pk_bf16_f32 v157, v54, v55
	s_waitcnt lgkmcnt(3)
	v_mfma_f32_32x32x16_bf16 v[32:47], v[146:149], v[154:157], v[32:47]
	s_waitcnt lgkmcnt(2)
	v_mfma_f32_32x32x16_bf16 v[16:31], v[150:153], v[154:157], v[16:31]
	v_cvt_pk_bf16_f32 v146, v56, v57
	v_cvt_pk_bf16_f32 v147, v58, v59
	v_cvt_pk_bf16_f32 v148, v60, v61
	v_cvt_pk_bf16_f32 v149, v62, v63
	s_waitcnt lgkmcnt(1)
	v_mfma_f32_32x32x16_bf16 v[32:47], v[138:141], v[146:149], v[32:47]
	s_waitcnt lgkmcnt(0)
	v_mfma_f32_32x32x16_bf16 v[16:31], v[142:145], v[146:149], v[16:31]
	s_andn2_b64 vcc, exec, s[20:21]
	s_cbranch_vccnz .LBB0_877
	s_waitcnt vmcnt(1)
	ds_write_b128 v132, v[104:107]
	s_waitcnt vmcnt(0)
	ds_write_b128 v133, v[108:111] offset:9216
	s_branch .LBB0_877
